# speedup vs baseline: 1.0299x; 1.0199x over previous
.LBB0_459:
	s_or_saveexec_b64 s[16:17], s[4:5]
	s_nop 0
	v_lshlrev_b32_e32 v128, 2, v157
	v_and_b32_e32 v143, 12, v128
	v_lshlrev_b32_e32 v128, 4, v156
	v_bitop3_b32 v136, v201, 63, v157 bitop3:0xc8
	s_movk_i32 s4, 0xffc0
	v_and_b32_e32 v138, 0xfffffc00, v128
	v_bitop3_b32 v137, v201, s4, v157 bitop3:0xc8
	v_bfe_u32 v139, v156, 2, 4
	v_add_u32_e32 v141, 0x80000, v138
	v_lshlrev_b32_e32 v145, 2, v136
	s_xor_b64 exec, exec, s[16:17]
	s_cbranch_execz .LBB0_463
	global_load_dword v128, v145, s[68:69]
	s_mov_b32 s4, 0x3f2aaaab
	s_cmp_eq_u32 s45, 0
	s_mov_b32 s18, 0
	s_mov_b32 s19, 56
	s_waitcnt vmcnt(0)
	v_mul_f32_e32 v128, 0xbfb8aa3b, v128
	v_exp_f32_e32 v130, v128
	s_nop 0
	v_add_f32_e32 v131, 1.0, v130
	v_add_f32_e32 v128, -1.0, v131
	v_sub_f32_e32 v129, v128, v131
	v_add_f32_e32 v129, 1.0, v129
	v_sub_f32_e32 v128, v130, v128
	v_add_f32_e32 v132, v128, v129
	v_frexp_mant_f32_e32 v128, v131
	v_cmp_gt_f32_e64 s[4:5], s4, v128
	v_cvt_f64_f32_e32 v[128:129], v131
	v_frexp_exp_i32_f64_e32 v128, v[128:129]
	v_subbrev_co_u32_e64 v128, s[4:5], 0, v128, s[4:5]
	v_sub_u32_e32 v129, 0, v128
	v_ldexp_f32 v131, v131, v129
	v_ldexp_f32 v129, v132, v129
	v_add_f32_e32 v132, -1.0, v131
	v_add_f32_e32 v133, 1.0, v132
	v_sub_f32_e32 v133, v131, v133
	v_add_f32_e32 v133, v129, v133
	v_add_f32_e32 v134, v132, v133
	v_sub_f32_e32 v132, v134, v132
	v_sub_f32_e32 v132, v133, v132
	v_add_f32_e32 v133, 1.0, v131
	v_add_f32_e32 v135, -1.0, v133
	v_sub_f32_e32 v131, v131, v135
	v_add_f32_e32 v129, v129, v131
	v_add_f32_e32 v131, v133, v129
	v_sub_f32_e32 v133, v131, v133
	v_sub_f32_e32 v129, v129, v133
	v_rcp_f32_e32 v133, v131
	v_cvt_f32_i32_e32 v128, v128
	s_mov_b32 s4, 0x3f317218
	v_mul_f32_e32 v135, v134, v133
	v_mul_f32_e32 v147, v131, v135
	v_fma_f32 v149, v135, v131, -v147
	v_fmac_f32_e32 v149, v135, v129
	v_add_f32_e32 v157, v147, v149
	v_sub_f32_e32 v200, v134, v157
	v_sub_f32_e32 v134, v134, v200
	v_sub_f32_e32 v147, v157, v147
	v_sub_f32_e32 v134, v134, v157
	v_add_f32_e32 v132, v132, v134
	v_sub_f32_e32 v134, v147, v149
	v_add_f32_e32 v132, v134, v132
	v_add_f32_e32 v134, v200, v132
	v_mul_f32_e32 v147, v133, v134
	v_mul_f32_e32 v149, v131, v147
	v_fma_f32 v131, v147, v131, -v149
	v_fmac_f32_e32 v131, v147, v129
	v_sub_f32_e32 v129, v200, v134
	v_add_f32_e32 v129, v132, v129
	v_add_f32_e32 v132, v149, v131
	v_sub_f32_e32 v157, v134, v132
	v_sub_f32_e32 v134, v134, v157
	v_sub_f32_e32 v149, v132, v149
	v_sub_f32_e32 v132, v134, v132
	v_add_f32_e32 v129, v129, v132
	v_sub_f32_e32 v131, v149, v131
	v_add_f32_e32 v129, v131, v129
	v_add_f32_e32 v131, v135, v147
	v_add_f32_e32 v129, v157, v129
	v_sub_f32_e32 v132, v131, v135
	v_mul_f32_e32 v129, v133, v129
	v_sub_f32_e32 v132, v147, v132
	v_add_f32_e32 v129, v132, v129
	v_mul_f32_e32 v135, 0x3f317218, v128
	v_add_f32_e32 v132, v131, v129
	v_fma_f32 v147, v128, s4, -v135
	v_mul_f32_e32 v133, v132, v132
	v_fmac_f32_e32 v147, 0xb102e308, v128
	v_sub_f32_e32 v128, v132, v131
	v_fmamk_f32 v134, v133, 0x3e9b6dac, v185
	v_sub_f32_e32 v128, v129, v128
	v_add_f32_e32 v129, v135, v147
	v_fmaak_f32 v134, v133, v134, 0x3f2aaada
	v_sub_f32_e32 v131, v129, v135
	v_ldexp_f32 v135, v132, 1
	v_mul_f32_e32 v132, v132, v133
	v_mul_f32_e32 v132, v132, v134
	v_add_f32_e32 v133, v135, v132
	v_sub_f32_e32 v134, v133, v135
	v_ldexp_f32 v128, v128, 1
	v_sub_f32_e32 v132, v132, v134
	v_add_f32_e32 v128, v128, v132
	v_add_f32_e32 v132, v133, v128
	v_sub_f32_e32 v133, v132, v133
	v_sub_f32_e32 v128, v128, v133
	v_add_f32_e32 v133, v129, v132
	v_sub_f32_e32 v134, v133, v129
	v_sub_f32_e32 v135, v133, v134
	v_sub_f32_e32 v131, v147, v131
	v_sub_f32_e32 v129, v129, v135
	v_sub_f32_e32 v132, v132, v134
	v_add_f32_e32 v129, v132, v129
	v_add_f32_e32 v132, v131, v128
	v_sub_f32_e32 v134, v132, v131
	v_sub_f32_e32 v135, v132, v134
	v_sub_f32_e32 v131, v131, v135
	v_sub_f32_e32 v128, v128, v134
	v_add_f32_e32 v129, v132, v129
	v_add_f32_e32 v128, v128, v131
	v_add_f32_e32 v131, v133, v129
	v_sub_f32_e32 v132, v131, v133
	v_sub_f32_e32 v129, v129, v132
	v_add_f32_e32 v128, v128, v129
	s_mov_b32 s4, 0x7f800000
	v_add_f32_e32 v128, v131, v128
	v_cmp_neq_f32_e64 s[4:5], s4, v130
	s_nop 1
	v_cndmask_b32_e64 v128, v187, v128, s[4:5]
	v_cmp_ngt_f32_e64 s[4:5], -1.0, v130
	s_nop 1
	v_cndmask_b32_e64 v128, v188, v128, s[4:5]
	v_cmp_neq_f32_e64 s[4:5], -1.0, v130
	s_nop 1
	v_cndmask_b32_e64 v128, v189, v128, s[4:5]
	s_mov_b32 s4, 0x33800000
	v_cmp_lt_f32_e64 s[4:5], |v130|, s4
	s_nop 1
	v_cndmask_b32_e64 v128, v128, v130, s[4:5]
	v_mul_f32_e32 v128, 0xc1000000, v128
	v_mul_f32_e32 v130, 0x3b808081, v128
	v_mov_b32_e32 v128, 0
	s_cselect_b64 s[4:5], -1, 0
	v_mov_b32_e32 v129, v128
	s_cmp_eq_u32 s45, 0
	s_cselect_b32 s34, 0, 0x3ff0
	v_lshlrev_b32_e32 v131, 8, v137
	v_lshl_or_b32 v131, v139, 4, v131
	v_or_b32_e32 v131, v131, v143
	v_or_b32_e32 v131, 0x10000, v131
	v_xor_b32_e32 v131, s34, v131
	s_mov_b32 s34, 0
	ds_read_b32 v226, v131
	v_xor_b32_e32 v243, 0x110, v131
	ds_read_b32 v227, v243
	v_xor_b32_e32 v244, 0x220, v131
	ds_read_b32 v228, v244
	v_xor_b32_e32 v245, 0x330, v131
	ds_read_b32 v229, v245
.Lgscan_q0:
	s_add_i32 s34, s34, 4
	s_lshl_b32 s35, s34, 8
	s_and_b32 vcc_lo, s34, 15
	s_lshl_b32 vcc_lo, vcc_lo, 4
	s_or_b32 s35, s35, vcc_lo
	v_xor_b32_e32 v132, s35, v131
	ds_read_b32 v230, v132
	v_xor_b32_e32 v243, 0x110, v132
	ds_read_b32 v231, v243
	v_xor_b32_e32 v244, 0x220, v132
	ds_read_b32 v232, v244
	v_xor_b32_e32 v245, 0x330, v132
	ds_read_b32 v233, v245
	s_waitcnt lgkmcnt(4)
	v_cvt_f32_f16_sdwa v234, v226 dst_sel:DWORD dst_unused:UNUSED_PAD src0_sel:WORD_1
	v_cvt_f32_f16_sdwa v235, v227 dst_sel:DWORD dst_unused:UNUSED_PAD src0_sel:WORD_1
	v_cvt_f32_f16_sdwa v236, v228 dst_sel:DWORD dst_unused:UNUSED_PAD src0_sel:WORD_1
	v_cvt_f32_f16_sdwa v237, v229 dst_sel:DWORD dst_unused:UNUSED_PAD src0_sel:WORD_1
	v_cvt_f32_f16_e32 v226, v226
	v_cvt_f32_f16_e32 v227, v227
	v_cvt_f32_f16_e32 v228, v228
	v_cvt_f32_f16_e32 v229, v229
	v_mul_f32_e32 v226, v130, v226
	v_mul_f32_e32 v227, v130, v227
	v_mul_f32_e32 v228, v130, v228
	v_mul_f32_e32 v229, v130, v229
	v_mul_f32_e32 v238, 0x3fb8aa3b, v226
	v_mul_f32_e32 v239, 0x3fb8aa3b, v227
	v_mul_f32_e32 v240, 0x3fb8aa3b, v228
	v_mul_f32_e32 v241, 0x3fb8aa3b, v229
	v_exp_f32_e32 v238, v238
	v_exp_f32_e32 v239, v239
	v_exp_f32_e32 v240, v240
	v_exp_f32_e32 v241, v241
	v_fma_f32 v242, -v238, v238, 1.0
	v_fma_f32 v243, -v239, v239, 1.0
	v_fma_f32 v244, -v240, v240, 1.0
	v_fma_f32 v245, -v241, v241, 1.0
	v_max_f32_e32 v242, 0, v242
	v_max_f32_e32 v243, 0, v243
	v_max_f32_e32 v244, 0, v244
	v_max_f32_e32 v245, 0, v245
	v_sqrt_f32_e32 v242, v242
	v_sqrt_f32_e32 v243, v243
	v_sqrt_f32_e32 v244, v244
	v_sqrt_f32_e32 v245, v245
	v_mul_f32_e32 v234, v242, v234
	v_mul_f32_e32 v235, v243, v235
	v_mul_f32_e32 v236, v244, v236
	v_mul_f32_e32 v237, v245, v237
	v_mul_f32_e32 v129, v129, v238
	v_add_f32_e32 v128, v128, v226
	v_add_f32_e32 v129, v129, v234
	v_mul_f32_e32 v129, v129, v239
	v_add_f32_e32 v128, v128, v227
	v_add_f32_e32 v129, v129, v235
	v_mul_f32_e32 v129, v129, v240
	v_add_f32_e32 v128, v128, v228
	v_add_f32_e32 v129, v129, v236
	v_mul_f32_e32 v129, v129, v241
	v_add_f32_e32 v128, v128, v229
	v_add_f32_e32 v129, v129, v237
	s_add_i32 s34, s34, 4
	s_lshl_b32 s35, s34, 8
	s_and_b32 vcc_lo, s34, 15
	s_lshl_b32 vcc_lo, vcc_lo, 4
	s_or_b32 s35, s35, vcc_lo
	v_xor_b32_e32 v132, s35, v131
	ds_read_b32 v226, v132
	v_xor_b32_e32 v243, 0x110, v132
	ds_read_b32 v227, v243
	v_xor_b32_e32 v244, 0x220, v132
	ds_read_b32 v228, v244
	v_xor_b32_e32 v245, 0x330, v132
	ds_read_b32 v229, v245
	s_waitcnt lgkmcnt(4)
	v_cvt_f32_f16_sdwa v234, v230 dst_sel:DWORD dst_unused:UNUSED_PAD src0_sel:WORD_1
	v_cvt_f32_f16_sdwa v235, v231 dst_sel:DWORD dst_unused:UNUSED_PAD src0_sel:WORD_1
	v_cvt_f32_f16_sdwa v236, v232 dst_sel:DWORD dst_unused:UNUSED_PAD src0_sel:WORD_1
	v_cvt_f32_f16_sdwa v237, v233 dst_sel:DWORD dst_unused:UNUSED_PAD src0_sel:WORD_1
	v_cvt_f32_f16_e32 v230, v230
	v_cvt_f32_f16_e32 v231, v231
	v_cvt_f32_f16_e32 v232, v232
	v_cvt_f32_f16_e32 v233, v233
	v_mul_f32_e32 v230, v130, v230
	v_mul_f32_e32 v231, v130, v231
	v_mul_f32_e32 v232, v130, v232
	v_mul_f32_e32 v233, v130, v233
	v_mul_f32_e32 v238, 0x3fb8aa3b, v230
	v_mul_f32_e32 v239, 0x3fb8aa3b, v231
	v_mul_f32_e32 v240, 0x3fb8aa3b, v232
	v_mul_f32_e32 v241, 0x3fb8aa3b, v233
	v_exp_f32_e32 v238, v238
	v_exp_f32_e32 v239, v239
	v_exp_f32_e32 v240, v240
	v_exp_f32_e32 v241, v241
	v_fma_f32 v242, -v238, v238, 1.0
	v_fma_f32 v243, -v239, v239, 1.0
	v_fma_f32 v244, -v240, v240, 1.0
	v_fma_f32 v245, -v241, v241, 1.0
	v_max_f32_e32 v242, 0, v242
	v_max_f32_e32 v243, 0, v243
	v_max_f32_e32 v244, 0, v244
	v_max_f32_e32 v245, 0, v245
	v_sqrt_f32_e32 v242, v242
	v_sqrt_f32_e32 v243, v243
	v_sqrt_f32_e32 v244, v244
	v_sqrt_f32_e32 v245, v245
	v_mul_f32_e32 v234, v242, v234
	v_mul_f32_e32 v235, v243, v235
	v_mul_f32_e32 v236, v244, v236
	v_mul_f32_e32 v237, v245, v237
	v_mul_f32_e32 v129, v129, v238
	v_add_f32_e32 v128, v128, v230
	v_add_f32_e32 v129, v129, v234
	v_mul_f32_e32 v129, v129, v239
	v_add_f32_e32 v128, v128, v231
	v_add_f32_e32 v129, v129, v235
	v_mul_f32_e32 v129, v129, v240
	v_add_f32_e32 v128, v128, v232
	v_add_f32_e32 v129, v129, v236
	v_mul_f32_e32 v129, v129, v241
	v_add_f32_e32 v128, v128, v233
	v_add_f32_e32 v129, v129, v237
	s_cmp_lt_u32 s34, 64
	s_cbranch_scc1 .Lgscan_q0
	s_waitcnt lgkmcnt(0)
	v_mul_f32_e32 v128, 0x3fb8aa3b, v128
	v_exp_f32_e32 v128, v128
	v_or_b32_e32 v130, v138, v136
	v_ashrrev_i32_e32 v131, 31, v130
	v_lshl_add_u64 v[130:131], v[130:131], 2, s[14:15]
	global_store_dword v[130:131], v128, off
	v_or_b32_e32 v130, v141, v136
	v_ashrrev_i32_e32 v131, 31, v130
	v_lshl_add_u64 v[130:131], v[130:131], 2, s[14:15]
	v_mov_b32_e32 v200, v156
	global_store_dword v[130:131], v129, off

.LBB0_465:
	s_andn2_saveexec_b64 s[4:5], s[4:5]
	s_cbranch_execz .LBB0_469
	global_load_dword v128, v145, s[68:69] offset:256
	s_mov_b32 s8, 0x3f2aaaab
	s_cmp_eq_u32 s45, 0
	s_mov_b32 s16, 0
	s_mov_b32 s17, 56
	s_waitcnt vmcnt(0)
	v_mul_f32_e32 v128, 0xbfb8aa3b, v128
	v_exp_f32_e32 v130, v128
	s_nop 0
	v_add_f32_e32 v131, 1.0, v130
	v_add_f32_e32 v128, -1.0, v131
	v_sub_f32_e32 v129, v128, v131
	v_add_f32_e32 v129, 1.0, v129
	v_sub_f32_e32 v128, v130, v128
	v_add_f32_e32 v132, v128, v129
	v_frexp_mant_f32_e32 v128, v131
	v_cmp_gt_f32_e32 vcc, s8, v128
	v_cvt_f64_f32_e32 v[128:129], v131
	v_frexp_exp_i32_f64_e32 v128, v[128:129]
	v_subbrev_co_u32_e32 v128, vcc, 0, v128, vcc
	v_sub_u32_e32 v129, 0, v128
	v_ldexp_f32 v131, v131, v129
	v_ldexp_f32 v129, v132, v129
	v_add_f32_e32 v132, -1.0, v131
	v_add_f32_e32 v133, 1.0, v132
	v_sub_f32_e32 v133, v131, v133
	v_add_f32_e32 v133, v129, v133
	v_add_f32_e32 v134, v132, v133
	v_sub_f32_e32 v132, v134, v132
	v_sub_f32_e32 v132, v133, v132
	v_add_f32_e32 v133, 1.0, v131
	v_add_f32_e32 v135, -1.0, v133
	v_sub_f32_e32 v131, v131, v135
	v_add_f32_e32 v129, v129, v131
	v_add_f32_e32 v131, v133, v129
	v_sub_f32_e32 v133, v131, v133
	v_sub_f32_e32 v129, v129, v133
	v_rcp_f32_e32 v133, v131
	v_cvt_f32_i32_e32 v128, v128
	s_mov_b32 s8, 0x3f317218
	v_mul_f32_e32 v135, v134, v133
	v_mul_f32_e32 v140, v131, v135
	v_fma_f32 v142, v135, v131, -v140
	v_fmac_f32_e32 v142, v135, v129
	v_add_f32_e32 v144, v140, v142
	v_sub_f32_e32 v145, v134, v144
	v_sub_f32_e32 v134, v134, v145
	v_sub_f32_e32 v140, v144, v140
	v_sub_f32_e32 v134, v134, v144
	v_add_f32_e32 v132, v132, v134
	v_sub_f32_e32 v134, v140, v142
	v_add_f32_e32 v132, v134, v132
	v_add_f32_e32 v134, v145, v132
	v_mul_f32_e32 v140, v133, v134
	v_mul_f32_e32 v142, v131, v140
	v_fma_f32 v131, v140, v131, -v142
	v_fmac_f32_e32 v131, v140, v129
	v_sub_f32_e32 v129, v145, v134
	v_add_f32_e32 v129, v132, v129
	v_add_f32_e32 v132, v142, v131
	v_sub_f32_e32 v144, v134, v132
	v_sub_f32_e32 v134, v134, v144
	v_sub_f32_e32 v142, v132, v142
	v_sub_f32_e32 v132, v134, v132
	v_add_f32_e32 v129, v129, v132
	v_sub_f32_e32 v131, v142, v131
	v_add_f32_e32 v129, v131, v129
	v_add_f32_e32 v131, v135, v140
	v_add_f32_e32 v129, v144, v129
	v_sub_f32_e32 v132, v131, v135
	v_mul_f32_e32 v129, v133, v129
	v_sub_f32_e32 v132, v140, v132
	v_add_f32_e32 v129, v132, v129
	v_mul_f32_e32 v135, 0x3f317218, v128
	v_add_f32_e32 v132, v131, v129
	v_fma_f32 v140, v128, s8, -v135
	v_mul_f32_e32 v133, v132, v132
	v_fmac_f32_e32 v140, 0xb102e308, v128
	v_sub_f32_e32 v128, v132, v131
	v_fmamk_f32 v134, v133, 0x3e9b6dac, v185
	v_sub_f32_e32 v128, v129, v128
	v_add_f32_e32 v129, v135, v140
	v_fmaak_f32 v134, v133, v134, 0x3f2aaada
	v_sub_f32_e32 v131, v129, v135
	v_ldexp_f32 v135, v132, 1
	v_mul_f32_e32 v132, v132, v133
	v_mul_f32_e32 v132, v132, v134
	v_add_f32_e32 v133, v135, v132
	v_sub_f32_e32 v134, v133, v135
	v_ldexp_f32 v128, v128, 1
	v_sub_f32_e32 v132, v132, v134
	v_add_f32_e32 v128, v128, v132
	v_add_f32_e32 v132, v133, v128
	v_sub_f32_e32 v133, v132, v133
	v_sub_f32_e32 v128, v128, v133
	v_add_f32_e32 v133, v129, v132
	v_sub_f32_e32 v134, v133, v129
	v_sub_f32_e32 v135, v133, v134
	v_sub_f32_e32 v131, v140, v131
	v_sub_f32_e32 v129, v129, v135
	v_sub_f32_e32 v132, v132, v134
	v_add_f32_e32 v129, v132, v129
	v_add_f32_e32 v132, v131, v128
	v_sub_f32_e32 v134, v132, v131
	v_sub_f32_e32 v135, v132, v134
	v_sub_f32_e32 v131, v131, v135
	v_sub_f32_e32 v128, v128, v134
	v_add_f32_e32 v129, v132, v129
	v_add_f32_e32 v128, v128, v131
	v_add_f32_e32 v131, v133, v129
	v_sub_f32_e32 v132, v131, v133
	v_sub_f32_e32 v129, v129, v132
	v_add_f32_e32 v128, v128, v129
	s_mov_b32 s8, 0x7f800000
	v_add_f32_e32 v128, v131, v128
	v_cmp_neq_f32_e32 vcc, s8, v130
	s_mov_b32 s8, 0x33800000
	s_nop 0
	v_cndmask_b32_e32 v128, v187, v128, vcc
	v_cmp_ngt_f32_e32 vcc, -1.0, v130
	s_nop 1
	v_cndmask_b32_e32 v128, v188, v128, vcc
	v_cmp_neq_f32_e32 vcc, -1.0, v130
	s_nop 1
	v_cndmask_b32_e32 v128, v189, v128, vcc
	v_cmp_lt_f32_e64 vcc, |v130|, s8
	s_cselect_b64 s[8:9], -1, 0
	s_nop 0
	v_cndmask_b32_e32 v128, v128, v130, vcc
	v_mul_f32_e32 v128, 0xc1000000, v128
	v_mul_f32_e32 v130, 0x3b808081, v128
	v_mov_b32_e32 v128, 0
	v_mov_b32_e32 v129, v128
	s_cmp_eq_u32 s45, 0
	s_cselect_b32 s34, 0, 0x3ff0
	v_lshlrev_b32_e32 v131, 8, v137
	v_lshl_or_b32 v131, v139, 4, v131
	v_or_b32_e32 v131, v131, v143
	v_or_b32_e32 v131, 0x10000, v131
	v_xor_b32_e32 v131, s34, v131
	s_mov_b32 s34, 0
	ds_read_b32 v226, v131
	v_xor_b32_e32 v243, 0x110, v131
	ds_read_b32 v227, v243
	v_xor_b32_e32 v244, 0x220, v131
	ds_read_b32 v228, v244
	v_xor_b32_e32 v245, 0x330, v131
	ds_read_b32 v229, v245
.Lgscan_q1:
	s_add_i32 s34, s34, 4
	s_lshl_b32 s35, s34, 8
	s_and_b32 vcc_lo, s34, 15
	s_lshl_b32 vcc_lo, vcc_lo, 4
	s_or_b32 s35, s35, vcc_lo
	v_xor_b32_e32 v132, s35, v131
	ds_read_b32 v230, v132
	v_xor_b32_e32 v243, 0x110, v132
	ds_read_b32 v231, v243
	v_xor_b32_e32 v244, 0x220, v132
	ds_read_b32 v232, v244
	v_xor_b32_e32 v245, 0x330, v132
	ds_read_b32 v233, v245
	s_waitcnt lgkmcnt(4)
	v_cvt_f32_f16_sdwa v234, v226 dst_sel:DWORD dst_unused:UNUSED_PAD src0_sel:WORD_1
	v_cvt_f32_f16_sdwa v235, v227 dst_sel:DWORD dst_unused:UNUSED_PAD src0_sel:WORD_1
	v_cvt_f32_f16_sdwa v236, v228 dst_sel:DWORD dst_unused:UNUSED_PAD src0_sel:WORD_1
	v_cvt_f32_f16_sdwa v237, v229 dst_sel:DWORD dst_unused:UNUSED_PAD src0_sel:WORD_1
	v_cvt_f32_f16_e32 v226, v226
	v_cvt_f32_f16_e32 v227, v227
	v_cvt_f32_f16_e32 v228, v228
	v_cvt_f32_f16_e32 v229, v229
	v_mul_f32_e32 v226, v130, v226
	v_mul_f32_e32 v227, v130, v227
	v_mul_f32_e32 v228, v130, v228
	v_mul_f32_e32 v229, v130, v229
	v_mul_f32_e32 v238, 0x3fb8aa3b, v226
	v_mul_f32_e32 v239, 0x3fb8aa3b, v227
	v_mul_f32_e32 v240, 0x3fb8aa3b, v228
	v_mul_f32_e32 v241, 0x3fb8aa3b, v229
	v_exp_f32_e32 v238, v238
	v_exp_f32_e32 v239, v239
	v_exp_f32_e32 v240, v240
	v_exp_f32_e32 v241, v241
	v_fma_f32 v242, -v238, v238, 1.0
	v_fma_f32 v243, -v239, v239, 1.0
	v_fma_f32 v244, -v240, v240, 1.0
	v_fma_f32 v245, -v241, v241, 1.0
	v_max_f32_e32 v242, 0, v242
	v_max_f32_e32 v243, 0, v243
	v_max_f32_e32 v244, 0, v244
	v_max_f32_e32 v245, 0, v245
	v_sqrt_f32_e32 v242, v242
	v_sqrt_f32_e32 v243, v243
	v_sqrt_f32_e32 v244, v244
	v_sqrt_f32_e32 v245, v245
	v_mul_f32_e32 v234, v242, v234
	v_mul_f32_e32 v235, v243, v235
	v_mul_f32_e32 v236, v244, v236
	v_mul_f32_e32 v237, v245, v237
	v_mul_f32_e32 v129, v129, v238
	v_add_f32_e32 v128, v128, v226
	v_add_f32_e32 v129, v129, v234
	v_mul_f32_e32 v129, v129, v239
	v_add_f32_e32 v128, v128, v227
	v_add_f32_e32 v129, v129, v235
	v_mul_f32_e32 v129, v129, v240
	v_add_f32_e32 v128, v128, v228
	v_add_f32_e32 v129, v129, v236
	v_mul_f32_e32 v129, v129, v241
	v_add_f32_e32 v128, v128, v229
	v_add_f32_e32 v129, v129, v237
	s_add_i32 s34, s34, 4
	s_lshl_b32 s35, s34, 8
	s_and_b32 vcc_lo, s34, 15
	s_lshl_b32 vcc_lo, vcc_lo, 4
	s_or_b32 s35, s35, vcc_lo
	v_xor_b32_e32 v132, s35, v131
	ds_read_b32 v226, v132
	v_xor_b32_e32 v243, 0x110, v132
	ds_read_b32 v227, v243
	v_xor_b32_e32 v244, 0x220, v132
	ds_read_b32 v228, v244
	v_xor_b32_e32 v245, 0x330, v132
	ds_read_b32 v229, v245
	s_waitcnt lgkmcnt(4)
	v_cvt_f32_f16_sdwa v234, v230 dst_sel:DWORD dst_unused:UNUSED_PAD src0_sel:WORD_1
	v_cvt_f32_f16_sdwa v235, v231 dst_sel:DWORD dst_unused:UNUSED_PAD src0_sel:WORD_1
	v_cvt_f32_f16_sdwa v236, v232 dst_sel:DWORD dst_unused:UNUSED_PAD src0_sel:WORD_1
	v_cvt_f32_f16_sdwa v237, v233 dst_sel:DWORD dst_unused:UNUSED_PAD src0_sel:WORD_1
	v_cvt_f32_f16_e32 v230, v230
	v_cvt_f32_f16_e32 v231, v231
	v_cvt_f32_f16_e32 v232, v232
	v_cvt_f32_f16_e32 v233, v233
	v_mul_f32_e32 v230, v130, v230
	v_mul_f32_e32 v231, v130, v231
	v_mul_f32_e32 v232, v130, v232
	v_mul_f32_e32 v233, v130, v233
	v_mul_f32_e32 v238, 0x3fb8aa3b, v230
	v_mul_f32_e32 v239, 0x3fb8aa3b, v231
	v_mul_f32_e32 v240, 0x3fb8aa3b, v232
	v_mul_f32_e32 v241, 0x3fb8aa3b, v233
	v_exp_f32_e32 v238, v238
	v_exp_f32_e32 v239, v239
	v_exp_f32_e32 v240, v240
	v_exp_f32_e32 v241, v241
	v_fma_f32 v242, -v238, v238, 1.0
	v_fma_f32 v243, -v239, v239, 1.0
	v_fma_f32 v244, -v240, v240, 1.0
	v_fma_f32 v245, -v241, v241, 1.0
	v_max_f32_e32 v242, 0, v242
	v_max_f32_e32 v243, 0, v243
	v_max_f32_e32 v244, 0, v244
	v_max_f32_e32 v245, 0, v245
	v_sqrt_f32_e32 v242, v242
	v_sqrt_f32_e32 v243, v243
	v_sqrt_f32_e32 v244, v244
	v_sqrt_f32_e32 v245, v245
	v_mul_f32_e32 v234, v242, v234
	v_mul_f32_e32 v235, v243, v235
	v_mul_f32_e32 v236, v244, v236
	v_mul_f32_e32 v237, v245, v237
	v_mul_f32_e32 v129, v129, v238
	v_add_f32_e32 v128, v128, v230
	v_add_f32_e32 v129, v129, v234
	v_mul_f32_e32 v129, v129, v239
	v_add_f32_e32 v128, v128, v231
	v_add_f32_e32 v129, v129, v235
	v_mul_f32_e32 v129, v129, v240
	v_add_f32_e32 v128, v128, v232
	v_add_f32_e32 v129, v129, v236
	v_mul_f32_e32 v129, v129, v241
	v_add_f32_e32 v128, v128, v233
	v_add_f32_e32 v129, v129, v237
	s_cmp_lt_u32 s34, 64
	s_cbranch_scc1 .Lgscan_q1
	s_waitcnt lgkmcnt(0)
	v_mul_f32_e32 v128, 0x3fb8aa3b, v128
	v_exp_f32_e32 v128, v128
	v_ashrrev_i32_e32 v139, 31, v138
	v_mov_b32_e32 v137, v164
	v_lshl_add_u64 v[130:131], v[136:137], 0, v[138:139]
	v_lshl_add_u64 v[130:131], v[130:131], 2, s[14:15]
	global_store_dword v[130:131], v128, off offset:256
	v_or3_b32 v130, v136, v141, 64
	v_ashrrev_i32_e32 v131, 31, v130
	v_lshl_add_u64 v[130:131], v[130:131], 2, s[14:15]
	global_store_dword v[130:131], v129, off
